# v65 plus attention item start: packed accumulator zeroing and first wait+barrier moved below the register-only setup
# speedup vs baseline: 1.0091x; 1.0017x over previous
; __device__ __forceinline__ void wait_all_barrier() { asm volatile("s_waitcnt vmcnt(0) lgkmcnt(0)\n\ts_barrier" ::: "memory"); }
; #define LOAD_PAIR(stage, s0) do { _Pragma("unroll") for (int i_ = 0; i_ < 4; ++i_) { const bf16* src_ = kvsrc[i_] + (size_t)(s0) * INW; \
;         dma16(src_, lds + (stage) + pofs[i_]); dma16(src_ + 768, lds + (stage) + 32768 + pofs[i_]); } } while (0)
; __device__ __forceinline__ int diff_item(ldsp lds, int qt, int bh, bool pre, unsigned* nctr, const bf16* U, bf16* O, const float* subw, float lam, float omlinit, float M0, int wave, int lane) {
;     ...
;     f32x16 o[4];
; #pragma unroll
;     for (int et = 0; et < 4; ++et)
; #pragma unroll
;         for (int i = 0; i < 16; ++i) o[et][i] = 0.f;
;     float lsum = 0.f;
;     const float nslope2 = -exp2f(-8.0f * (float)(h + 1) / 6.0f) * LOG2E;
;     const int jmax = 2 * qt + (wq >> 1);
;     const unsigned lds0 = (unsigned)(size_t)lds; LaneAddr LA; lane_addr<4>(LA, 8 * c, 0, lane);
;     const int prow = lane >> 4, chp = lane & 15;
;     const bf16* kvsrc[4]; int pofs[4];
; #pragma unroll
;     for (int i = 0; i < 4; ++i) { const int pi = wave * 4 + i, row = 4 * pi + prow; const unsigned ch = (unsigned)chp ^ (((unsigned)prow << 2) | ((unsigned)pi & 3u));
;         kvsrc[i] = U + (tokbase + row) * INW + 768 + h * 128 + ch * 8; pofs[i] = 1024 * pi; }
;     ...
;     if (!pre) LOAD_PAIR(0, 0);
;     wait_all_barrier();
;     for (int p = 0; p < qt; ++p) {
;         const int stage = (p & 1) * 65536;
;         LOAD_PAIR(((p + 1) & 1) * 65536, 128 * (p + 1)); if (PROBE == 6) LOAD_PAIR(((p + 1) & 1) * 65536, 128 * (p + 1));
;         attn_pair<true>(o, lsum, qf, LA, lds0 + stage, lds0 + stage + 32768, lds0 + stage + 16384, lds0 + stage + 32768 + 16384, nslope2, -M0, (float)(t0 + r - 128 * p - 4 * hh), (float)(t0 + r - 128 * p - 64 - 4 * hh));
.LBB0_807:
	s_add_i32 s73, s73, 1
	v_cvt_f32_i32_e32 v0, s73
	v_mov_b32_e32 v15, 0
	v_mov_b32_e32 v14, v15
	v_mul_f32_e32 v0, 0xc1000000, v0
	v_div_scale_f32 v1, s[14:15], s30, s30, v0
	v_rcp_f32_e32 v2, v1
	v_div_scale_f32 v3, vcc, v0, s30, v0
	s_mov_b32 s14, 0xc2fc0000
	v_fma_f32 v4, -v1, v2, 1.0
	v_fmac_f32_e32 v2, v4, v2
	v_mul_f32_e32 v4, v3, v2
	v_fma_f32 v5, -v1, v4, v3
	v_fmac_f32_e32 v4, v5, v2
	v_fma_f32 v1, -v1, v4, v3
	v_div_fmas_f32 v1, v1, v2, v4
	v_div_fixup_f32 v0, v1, s30, v0
	v_cmp_gt_f32_e32 vcc, s14, v0
	s_and_b64 s[14:15], vcc, exec
	s_cselect_b32 s14, 0xffffffc0, 0
	v_cndmask_b32_e32 v1, 0, v212, vcc
	v_add_f32_e32 v0, v0, v1
	v_exp_f32_e32 v0, v0
	s_cmp_eq_u32 s80, 0
	v_pk_mov_b32 v[12:13], v[14:15], v[14:15]
	v_ldexp_f32 v0, v0, s14
	v_mul_f32_e32 v200, 0xbfb8aa3b, v0
	v_pk_mov_b32 v[10:11], v[14:15], v[14:15]
	v_pk_mov_b32 v[8:9], v[14:15], v[14:15]
	v_pk_mov_b32 v[6:7], v[14:15], v[14:15]
	v_pk_mov_b32 v[4:5], v[14:15], v[14:15]
	v_pk_mov_b32 v[2:3], v[14:15], v[14:15]
	v_pk_mov_b32 v[0:1], v[14:15], v[14:15]
	v_pk_mov_b32 v[30:31], v[14:15], v[14:15]
	v_pk_mov_b32 v[28:29], v[14:15], v[14:15]
	v_pk_mov_b32 v[26:27], v[14:15], v[14:15]
	v_pk_mov_b32 v[24:25], v[14:15], v[14:15]
	v_pk_mov_b32 v[22:23], v[14:15], v[14:15]
	v_pk_mov_b32 v[20:21], v[14:15], v[14:15]
	v_pk_mov_b32 v[18:19], v[14:15], v[14:15]
	v_pk_mov_b32 v[16:17], v[14:15], v[14:15]
	v_pk_mov_b32 v[46:47], v[14:15], v[14:15]
	v_pk_mov_b32 v[44:45], v[14:15], v[14:15]
	v_pk_mov_b32 v[42:43], v[14:15], v[14:15]
	v_pk_mov_b32 v[40:41], v[14:15], v[14:15]
	v_pk_mov_b32 v[38:39], v[14:15], v[14:15]
	v_pk_mov_b32 v[36:37], v[14:15], v[14:15]
	v_pk_mov_b32 v[34:35], v[14:15], v[14:15]
	v_pk_mov_b32 v[32:33], v[14:15], v[14:15]
	v_pk_mov_b32 v[62:63], v[14:15], v[14:15]
	v_pk_mov_b32 v[60:61], v[14:15], v[14:15]
	v_pk_mov_b32 v[58:59], v[14:15], v[14:15]
	v_pk_mov_b32 v[56:57], v[14:15], v[14:15]
	v_pk_mov_b32 v[54:55], v[14:15], v[14:15]
	v_pk_mov_b32 v[52:53], v[14:15], v[14:15]
	v_pk_mov_b32 v[50:51], v[14:15], v[14:15]
	v_pk_mov_b32 v[48:49], v[14:15], v[14:15]
	v_mov_b32_e32 v195, v15
	s_waitcnt vmcnt(0) lgkmcnt(0)
	s_barrier
	s_cbranch_scc1 .LBB0_810
	v_mov_b32_e32 v195, 0
	v_lshl_add_u32 v193, s72, 7, v208
	s_mov_b32 s24, 0x10000
	s_movk_i32 s70, 0x80
	s_mov_b32 s71, s80
	v_mov_b32_e32 v0, 0
	v_mov_b32_e32 v1, v195
	v_mov_b32_e32 v2, v195
	v_mov_b32_e32 v3, v195
	v_mov_b32_e32 v4, v195
	v_mov_b32_e32 v5, v195
	v_mov_b32_e32 v6, v195
	v_mov_b32_e32 v7, v195
	v_mov_b32_e32 v8, v195
	v_mov_b32_e32 v9, v195
	v_mov_b32_e32 v10, v195
	v_mov_b32_e32 v11, v195
	v_mov_b32_e32 v12, v195
	v_mov_b32_e32 v13, v195
	v_mov_b32_e32 v14, v195
	v_mov_b32_e32 v15, v195
	v_mov_b32_e32 v16, 0
	v_mov_b32_e32 v17, v195
	v_mov_b32_e32 v18, v195
	v_mov_b32_e32 v19, v195
	v_mov_b32_e32 v20, v195
	v_mov_b32_e32 v21, v195
	v_mov_b32_e32 v22, v195
	v_mov_b32_e32 v23, v195
	v_mov_b32_e32 v24, v195
	v_mov_b32_e32 v25, v195
	v_mov_b32_e32 v26, v195
	v_mov_b32_e32 v27, v195
	v_mov_b32_e32 v28, v195
	v_mov_b32_e32 v29, v195
	v_mov_b32_e32 v30, v195
	v_mov_b32_e32 v31, v195
	v_mov_b32_e32 v32, 0
	v_mov_b32_e32 v33, v195
	v_mov_b32_e32 v34, v195
	v_mov_b32_e32 v35, v195
	v_mov_b32_e32 v36, v195
	v_mov_b32_e32 v37, v195
	v_mov_b32_e32 v38, v195
	v_mov_b32_e32 v39, v195
	v_mov_b32_e32 v40, v195
	v_mov_b32_e32 v41, v195
	v_mov_b32_e32 v42, v195
	v_mov_b32_e32 v43, v195
	v_mov_b32_e32 v44, v195
	v_mov_b32_e32 v45, v195
	v_mov_b32_e32 v46, v195
	v_mov_b32_e32 v47, v195
	v_mov_b32_e32 v48, 0
	v_mov_b32_e32 v49, v195
	v_mov_b32_e32 v50, v195
	v_mov_b32_e32 v51, v195
	v_mov_b32_e32 v52, v195
	v_mov_b32_e32 v53, v195
	v_mov_b32_e32 v54, v195
	v_mov_b32_e32 v55, v195
	v_mov_b32_e32 v56, v195
	v_mov_b32_e32 v57, v195
	v_mov_b32_e32 v58, v195
	v_mov_b32_e32 v59, v195
	v_mov_b32_e32 v60, v195
	v_mov_b32_e32 v61, v195
	v_mov_b32_e32 v62, v195
	v_mov_b32_e32 v63, v195

; __device__ __forceinline__ void wait_all_barrier() { asm volatile("s_waitcnt vmcnt(0) lgkmcnt(0)\n\ts_barrier" ::: "memory"); }
; #define LOAD_PAIR(stage, s0) do { _Pragma("unroll") for (int i_ = 0; i_ < 4; ++i_) { const bf16* src_ = kvsrc[i_] + (size_t)(s0) * INW; \
;         dma16(src_, lds + (stage) + pofs[i_]); dma16(src_ + 768, lds + (stage) + 32768 + pofs[i_]); } } while (0)
; __device__ __forceinline__ int diff_item(ldsp lds, int qt, int bh, bool pre, unsigned* nctr, const bf16* U, bf16* O, const float* subw, float lam, float omlinit, float M0, int wave, int lane) {
;     ...
;     f32x16 o[4];
; #pragma unroll
;     for (int et = 0; et < 4; ++et)
; #pragma unroll
;         for (int i = 0; i < 16; ++i) o[et][i] = 0.f;
;     float lsum = 0.f;
;     const float nslope2 = -exp2f(-8.0f * (float)(h + 1) / 6.0f) * LOG2E;
;     const int jmax = 2 * qt + (wq >> 1);
;     const unsigned lds0 = (unsigned)(size_t)lds; LaneAddr LA; lane_addr<4>(LA, 8 * c, 0, lane);
;     const int prow = lane >> 4, chp = lane & 15;
;     const bf16* kvsrc[4]; int pofs[4];
; #pragma unroll
;     for (int i = 0; i < 4; ++i) { const int pi = wave * 4 + i, row = 4 * pi + prow; const unsigned ch = (unsigned)chp ^ (((unsigned)prow << 2) | ((unsigned)pi & 3u));
;         kvsrc[i] = U + (tokbase + row) * INW + 768 + h * 128 + ch * 8; pofs[i] = 1024 * pi; }
;     ...
;     if (!pre) LOAD_PAIR(0, 0);
;     wait_all_barrier();
;     for (int p = 0; p < qt; ++p) {
;         const int stage = (p & 1) * 65536;
;         LOAD_PAIR(((p + 1) & 1) * 65536, 128 * (p + 1)); if (PROBE == 6) LOAD_PAIR(((p + 1) & 1) * 65536, 128 * (p + 1));
;         attn_pair<true>(o, lsum, qf, LA, lds0 + stage, lds0 + stage + 32768, lds0 + stage + 16384, lds0 + stage + 32768 + 16384, nslope2, -M0, (float)(t0 + r - 128 * p - 4 * hh), (float)(t0 + r - 128 * p - 64 - 4 * hh));
.LBB0_1851:
	s_add_i32 s67, s67, 1
	v_cvt_f32_i32_e32 v0, s67
	v_mov_b32_e32 v15, 0
	v_mov_b32_e32 v14, v15
	v_mul_f32_e32 v0, 0xc1000000, v0
	v_div_scale_f32 v1, s[4:5], s72, s72, v0
	v_rcp_f32_e32 v2, v1
	v_div_scale_f32 v3, vcc, v0, s72, v0
	s_mov_b32 s4, 0xc2fc0000
	v_fma_f32 v4, -v1, v2, 1.0
	v_fmac_f32_e32 v2, v4, v2
	v_mul_f32_e32 v4, v3, v2
	v_fma_f32 v5, -v1, v4, v3
	v_fmac_f32_e32 v4, v5, v2
	v_fma_f32 v1, -v1, v4, v3
	v_div_fmas_f32 v1, v1, v2, v4
	v_div_fixup_f32 v0, v1, s72, v0
	v_cmp_gt_f32_e32 vcc, s4, v0
	s_and_b64 s[4:5], vcc, exec
	s_cselect_b32 s4, 0xffffffc0, 0
	v_cndmask_b32_e32 v1, 0, v212, vcc
	v_add_f32_e32 v0, v0, v1
	v_exp_f32_e32 v0, v0
	s_cmp_eq_u32 s76, 0
	v_pk_mov_b32 v[12:13], v[14:15], v[14:15]
	v_ldexp_f32 v0, v0, s4
	v_mul_f32_e32 v200, 0xbfb8aa3b, v0
	v_pk_mov_b32 v[10:11], v[14:15], v[14:15]
	v_pk_mov_b32 v[8:9], v[14:15], v[14:15]
	v_pk_mov_b32 v[6:7], v[14:15], v[14:15]
	v_pk_mov_b32 v[4:5], v[14:15], v[14:15]
	v_pk_mov_b32 v[2:3], v[14:15], v[14:15]
	v_pk_mov_b32 v[0:1], v[14:15], v[14:15]
	v_pk_mov_b32 v[30:31], v[14:15], v[14:15]
	v_pk_mov_b32 v[28:29], v[14:15], v[14:15]
	v_pk_mov_b32 v[26:27], v[14:15], v[14:15]
	v_pk_mov_b32 v[24:25], v[14:15], v[14:15]
	v_pk_mov_b32 v[22:23], v[14:15], v[14:15]
	v_pk_mov_b32 v[20:21], v[14:15], v[14:15]
	v_pk_mov_b32 v[18:19], v[14:15], v[14:15]
	v_pk_mov_b32 v[16:17], v[14:15], v[14:15]
	v_pk_mov_b32 v[46:47], v[14:15], v[14:15]
	v_pk_mov_b32 v[44:45], v[14:15], v[14:15]
	v_pk_mov_b32 v[42:43], v[14:15], v[14:15]
	v_pk_mov_b32 v[40:41], v[14:15], v[14:15]
	v_pk_mov_b32 v[38:39], v[14:15], v[14:15]
	v_pk_mov_b32 v[36:37], v[14:15], v[14:15]
	v_pk_mov_b32 v[34:35], v[14:15], v[14:15]
	v_pk_mov_b32 v[32:33], v[14:15], v[14:15]
	v_pk_mov_b32 v[62:63], v[14:15], v[14:15]
	v_pk_mov_b32 v[60:61], v[14:15], v[14:15]
	v_pk_mov_b32 v[58:59], v[14:15], v[14:15]
	v_pk_mov_b32 v[56:57], v[14:15], v[14:15]
	v_pk_mov_b32 v[54:55], v[14:15], v[14:15]
	v_pk_mov_b32 v[52:53], v[14:15], v[14:15]
	v_pk_mov_b32 v[50:51], v[14:15], v[14:15]
	v_pk_mov_b32 v[48:49], v[14:15], v[14:15]
	v_mov_b32_e32 v195, v15
	s_waitcnt vmcnt(0) lgkmcnt(0)
	s_barrier
	s_cbranch_scc1 .LBB0_1854
	v_mov_b32_e32 v195, 0
	v_lshl_add_u32 v193, s66, 7, v208
	s_mov_b32 s22, 0x10000
	s_movk_i32 s64, 0x80
	s_mov_b32 s65, s76
	v_mov_b32_e32 v0, 0
	v_mov_b32_e32 v1, v195
	v_mov_b32_e32 v2, v195
	v_mov_b32_e32 v3, v195
	v_mov_b32_e32 v4, v195
	v_mov_b32_e32 v5, v195
	v_mov_b32_e32 v6, v195
	v_mov_b32_e32 v7, v195
	v_mov_b32_e32 v8, v195
	v_mov_b32_e32 v9, v195
	v_mov_b32_e32 v10, v195
	v_mov_b32_e32 v11, v195
	v_mov_b32_e32 v12, v195
	v_mov_b32_e32 v13, v195
	v_mov_b32_e32 v14, v195
	v_mov_b32_e32 v15, v195
	v_mov_b32_e32 v16, 0
	v_mov_b32_e32 v17, v195
	v_mov_b32_e32 v18, v195
	v_mov_b32_e32 v19, v195
	v_mov_b32_e32 v20, v195
	v_mov_b32_e32 v21, v195
	v_mov_b32_e32 v22, v195
	v_mov_b32_e32 v23, v195
	v_mov_b32_e32 v24, v195
	v_mov_b32_e32 v25, v195
	v_mov_b32_e32 v26, v195
	v_mov_b32_e32 v27, v195
	v_mov_b32_e32 v28, v195
	v_mov_b32_e32 v29, v195
	v_mov_b32_e32 v30, v195
	v_mov_b32_e32 v31, v195
	v_mov_b32_e32 v32, 0
	v_mov_b32_e32 v33, v195
	v_mov_b32_e32 v34, v195
	v_mov_b32_e32 v35, v195
	v_mov_b32_e32 v36, v195
	v_mov_b32_e32 v37, v195
	v_mov_b32_e32 v38, v195
	v_mov_b32_e32 v39, v195
	v_mov_b32_e32 v40, v195
	v_mov_b32_e32 v41, v195
	v_mov_b32_e32 v42, v195
	v_mov_b32_e32 v43, v195
	v_mov_b32_e32 v44, v195
	v_mov_b32_e32 v45, v195
	v_mov_b32_e32 v46, v195
	v_mov_b32_e32 v47, v195
	v_mov_b32_e32 v48, 0
	v_mov_b32_e32 v49, v195
	v_mov_b32_e32 v50, v195
	v_mov_b32_e32 v51, v195
	v_mov_b32_e32 v52, v195
	v_mov_b32_e32 v53, v195
	v_mov_b32_e32 v54, v195
	v_mov_b32_e32 v55, v195
	v_mov_b32_e32 v56, v195
	v_mov_b32_e32 v57, v195
	v_mov_b32_e32 v58, v195
	v_mov_b32_e32 v59, v195
	v_mov_b32_e32 v60, v195
	v_mov_b32_e32 v61, v195
	v_mov_b32_e32 v62, v195
	v_mov_b32_e32 v63, v195
